# attention loops: K/V tile loads use scalar base + 32-bit lane offset (no per-load 64-bit VALU adds / carry pair)
# speedup vs baseline: 1.0123x; 1.0123x over previous
.LBB0_925:
	s_or_b64 exec, exec, s[8:9]
	v_mad_u32_u24 v33, v32, s20, 0
	v_add_u32_e32 v192, v33, v168
	ds_read_b128 v[0:3], v192
	ds_read_b128 v[16:19], v192 offset:0x1a00
	ds_read_b128 v[34:37], v192 offset:32
	ds_read_b128 v[38:41], v192 offset:0x1a20
	ds_read_b128 v[42:45], v192 offset:64
	ds_read_b128 v[46:49], v192 offset:0x1a40
	ds_read_b128 v[50:53], v192 offset:96
	ds_read_b128 v[54:57], v192 offset:0x1a60
	ds_read_b128 v[58:61], v192 offset:128
	ds_read_b128 v[62:65], v192 offset:0x1a80
	ds_read_b128 v[66:69], v192 offset:160
	ds_read_b128 v[70:73], v192 offset:0x1aa0
	s_waitcnt lgkmcnt(0)
	v_lshlrev_b32_e32 v189, 3, v10
	v_mfma_f32_32x32x16_bf16 v[0:15], v[0:3], v[116:119], 0
	v_mul_u32_u24_e32 v190, 0xd0, v32
	v_mul_u32_u24_e32 v191, 0x88, v32
	v_mul_i32_i24_e32 v32, 0xffffffb8, v32
	v_add3_u32 v204, v33, v32, v189
	s_lshr_b32 s8, s15, 8
	s_and_b32 s9, s14, 56
	s_add_i32 s8, s8, s9
	v_mfma_f32_32x32x16_bf16 v[16:31], v[16:19], v[116:119], 0
	s_add_i32 s17, s8, s17
	s_movk_i32 s19, 0x1000
	s_mul_i32 s76, s17, 0x900
	s_lshl_b64 s[8:9], s[76:77], 7
	s_mul_i32 s17, s17, 0x6c000
	s_mul_hi_u32 s18, s76, 0xc0
	v_mov_b32_e32 v171, s9
	v_mfma_f32_32x32x16_bf16 v[0:15], v[34:37], v[112:115], v[0:15]
	v_mfma_f32_32x32x16_bf16 v[16:31], v[38:41], v[112:115], v[16:31]
	v_mfma_f32_32x32x16_bf16 v[0:15], v[42:45], v[108:111], v[0:15]
	v_mfma_f32_32x32x16_bf16 v[16:31], v[46:49], v[108:111], v[16:31]
	v_mfma_f32_32x32x16_bf16 v[0:15], v[50:53], v[104:107], v[0:15]
	v_mfma_f32_32x32x16_bf16 v[16:31], v[54:57], v[104:107], v[16:31]
	v_mfma_f32_32x32x16_bf16 v[0:15], v[58:61], v[100:103], v[0:15]
	v_mfma_f32_32x32x16_bf16 v[16:31], v[62:65], v[100:103], v[16:31]
	v_add_u32_e32 v64, 0x3400, v204
	ds_read_b64 v[60:61], v64
	ds_read_b64 v[62:63], v64 offset:16
	ds_read_b64 v[56:57], v64 offset:32
	ds_read_b64 v[58:59], v64 offset:48
	ds_read_b64 v[52:53], v64 offset:64
	ds_read_b64 v[54:55], v64 offset:80
	ds_read_b64 v[48:49], v64 offset:96
	ds_read_b64 v[50:51], v64 offset:112
	ds_read_b64 v[44:45], v64 offset:0x1100
	ds_read_b64 v[46:47], v64 offset:0x1110
	ds_read_b64 v[40:41], v64 offset:0x1120
	ds_read_b64 v[42:43], v64 offset:0x1130
	ds_read_b64 v[36:37], v64 offset:0x1140
	ds_read_b64 v[38:39], v64 offset:0x1150
	ds_read_b64 v[32:33], v64 offset:0x1160
	ds_read_b64 v[34:35], v64 offset:0x1170
	s_nop 0
	s_waitcnt lgkmcnt(0)
	v_mfma_f32_32x32x16_bf16 v[0:15], v[66:69], v[96:99], v[0:15]
	v_mfma_f32_32x32x16_bf16 v[16:31], v[70:73], v[96:99], v[16:31]
	s_nop 11
	v_max_f32_e32 v64, v0, v16
	v_max_f32_e32 v65, v1, v17
	v_max_f32_e32 v66, v3, v19
	v_max3_f32 v66, v2, v18, v66
	v_max3_f32 v64, v64, v65, v66
	v_max_f32_e32 v65, v5, v21
	v_max_f32_e32 v66, v7, v23
	v_max3_f32 v65, v4, v20, v65
	v_max3_f32 v66, v6, v22, v66
	v_max3_f32 v64, v64, v65, v66
	v_max_f32_e32 v65, v9, v25
	v_max_f32_e32 v66, v11, v27
	v_max3_f32 v65, v8, v24, v65
	v_max3_f32 v66, v10, v26, v66
	v_max3_f32 v64, v64, v65, v66
	v_max_f32_e32 v65, v13, v29
	v_max_f32_e32 v66, v15, v31
	v_max3_f32 v65, v12, v28, v65
	v_max3_f32 v66, v14, v30, v66
	v_max3_f32 v64, v64, v65, v66
	v_mov_b32_e32 v65, v64
	s_nop 1
	v_permlane32_swap_b32_e32 v64, v65
	v_max_f32_e32 v84, v64, v65
	v_sub_f32_e32 v0, v0, v84
	v_sub_f32_e32 v1, v1, v84
	v_sub_f32_e32 v16, v16, v84
	v_sub_f32_e32 v17, v17, v84
	v_exp_f32_e32 v0, v0
	v_exp_f32_e32 v1, v1
	v_sub_f32_e32 v64, v26, v84
	v_sub_f32_e32 v65, v27, v84
	v_sub_f32_e32 v26, v2, v84
	v_sub_f32_e32 v27, v3, v84
	v_exp_f32_e32 v2, v16
	v_exp_f32_e32 v3, v17
	v_sub_f32_e32 v18, v18, v84
	v_sub_f32_e32 v19, v19, v84
	v_sub_f32_e32 v68, v30, v84
	v_sub_f32_e32 v69, v31, v84
	v_sub_f32_e32 v30, v6, v84
	v_sub_f32_e32 v31, v7, v84
	v_exp_f32_e32 v6, v26
	v_exp_f32_e32 v7, v27
	v_sub_f32_e32 v66, v28, v84
	v_sub_f32_e32 v67, v29, v84
	v_sub_f32_e32 v28, v4, v84
	v_sub_f32_e32 v29, v5, v84
	v_sub_f32_e32 v70, v8, v84
	v_sub_f32_e32 v71, v9, v84
	v_exp_f32_e32 v8, v18
	v_exp_f32_e32 v9, v19
	v_sub_f32_e32 v20, v20, v84
	v_sub_f32_e32 v21, v21, v84
	v_sub_f32_e32 v72, v10, v84
	v_sub_f32_e32 v73, v11, v84
	v_pk_add_f32 v[4:5], v[0:1], 0 op_sel_hi:[1,0]
	v_exp_f32_e32 v10, v28
	v_exp_f32_e32 v11, v29
	v_sub_f32_e32 v74, v12, v84
	v_sub_f32_e32 v75, v13, v84
	v_pk_add_f32 v[4:5], v[2:3], v[4:5]
	v_exp_f32_e32 v12, v20
	v_exp_f32_e32 v13, v21
	v_sub_f32_e32 v22, v22, v84
	v_sub_f32_e32 v23, v23, v84
	v_sub_f32_e32 v85, v14, v84
	v_sub_f32_e32 v86, v15, v84
	v_pk_add_f32 v[4:5], v[6:7], v[4:5]
	v_exp_f32_e32 v14, v30
	v_exp_f32_e32 v15, v31
	v_pk_add_f32 v[4:5], v[8:9], v[4:5]
	v_exp_f32_e32 v20, v22
	v_exp_f32_e32 v21, v23
	v_sub_f32_e32 v24, v24, v84
	v_sub_f32_e32 v25, v25, v84
	v_pk_add_f32 v[4:5], v[10:11], v[4:5]
	v_exp_f32_e32 v22, v70
	v_exp_f32_e32 v23, v71
	v_pk_add_f32 v[4:5], v[12:13], v[4:5]
	v_exp_f32_e32 v24, v24
	v_exp_f32_e32 v25, v25
	v_pk_add_f32 v[4:5], v[14:15], v[4:5]
	v_exp_f32_e32 v26, v72
	v_exp_f32_e32 v27, v73
	v_pk_add_f32 v[4:5], v[20:21], v[4:5]
	v_exp_f32_e32 v28, v64
	v_exp_f32_e32 v29, v65
	v_pk_add_f32 v[4:5], v[22:23], v[4:5]
	v_exp_f32_e32 v30, v74
	v_exp_f32_e32 v31, v75
	v_pk_add_f32 v[4:5], v[24:25], v[4:5]
	v_exp_f32_e32 v66, v66
	v_exp_f32_e32 v67, v67
	v_pk_add_f32 v[4:5], v[26:27], v[4:5]
	v_exp_f32_e32 v64, v85
	v_exp_f32_e32 v65, v86
	v_pk_add_f32 v[4:5], v[28:29], v[4:5]
	v_exp_f32_e32 v92, v68
	v_exp_f32_e32 v93, v69
	v_pk_add_f32 v[4:5], v[30:31], v[4:5]
	v_cvt_pk_bf16_f32 v16, v0, v1
	v_pk_add_f32 v[4:5], v[66:67], v[4:5]
	v_cvt_pk_bf16_f32 v17, v6, v7
	v_pk_add_f32 v[4:5], v[64:65], v[4:5]
	v_cvt_pk_bf16_f32 v18, v10, v11
	v_pk_add_f32 v[4:5], v[92:93], v[4:5]
	v_cvt_pk_bf16_f32 v19, v14, v15
	v_pk_add_f32 v[86:87], v[4:5], v[4:5] op_sel_hi:[0,1]
	v_cvt_pk_bf16_f32 v72, v22, v23
	v_cvt_pk_bf16_f32 v73, v26, v27
	v_cvt_pk_bf16_f32 v74, v30, v31
	v_cvt_pk_bf16_f32 v75, v64, v65
	v_cvt_pk_bf16_f32 v68, v2, v3
	v_cvt_pk_bf16_f32 v69, v8, v9
	v_cvt_pk_bf16_f32 v70, v12, v13
	v_cvt_pk_bf16_f32 v71, v20, v21
	v_cvt_pk_bf16_f32 v64, v24, v25
	v_cvt_pk_bf16_f32 v65, v28, v29
	v_mfma_f32_32x32x16_bf16 v[0:15], v[60:63], v[16:19], 0
	v_cvt_pk_bf16_f32 v66, v66, v67
	v_cvt_pk_bf16_f32 v67, v92, v93
	v_mov_b32_e32 v85, v87
	v_add_f32_e64 v176, v84, 0
	v_add_f32_e64 v177, v85, 0
	v_mfma_f32_32x32x16_bf16 v[16:31], v[44:47], v[16:19], 0
	v_mfma_f32_32x32x16_bf16 v[0:15], v[56:59], v[72:75], v[0:15]
	v_mfma_f32_32x32x16_bf16 v[16:31], v[40:43], v[72:75], v[16:31]
	v_mfma_f32_32x32x16_bf16 v[0:15], v[52:55], v[68:71], v[0:15]
	v_mfma_f32_32x32x16_bf16 v[16:31], v[36:39], v[68:71], v[16:31]
	v_mfma_f32_32x32x16_bf16 v[0:15], v[48:51], v[64:67], v[0:15]
	v_add_f32_e64 v48, -v176, neg(0)
	v_add_f32_e64 v49, -v177, neg(0)
	v_mov_b32_e32 v49, v48
	v_mov_b32_e32 v50, v48
	v_mov_b32_e32 v51, v48
	v_mov_b32_e32 v52, v48
	v_mov_b32_e32 v53, v48
	v_mfma_f32_32x32x16_bf16 v[16:31], v[32:35], v[64:67], v[16:31]
	v_lshlrev_b32_e32 v32, 8, v90
	v_lshlrev_b32_e32 v33, 5, v88
	v_and_or_b32 v32, v33, s19, v32
	v_lshlrev_b32_e32 v33, 4, v89
	v_and_or_b32 v33, v88, 64, v33
	v_or3_b32 v170, s8, v32, v33
	s_add_u32 s8, s17, 0x12b06000
	s_addc_u32 s9, s18, 0
	v_lshl_add_u64 v[32:33], v[80:81], 1, s[8:9]
	v_lshl_add_u64 v[172:173], v[82:83], 1, v[32:33]
	v_lshl_add_u64 v[32:33], v[76:77], 1, s[8:9]
	v_lshl_add_u64 v[174:175], v[78:79], 1, v[32:33]
	s_mov_b32 s17, 0x8000
	v_mov_b32_e32 v54, v48
	v_mov_b32_e32 v55, v48
	v_mov_b32_e32 v56, v48
	v_mov_b32_e32 v57, v48
	v_mov_b32_e32 v58, v48
	v_mov_b32_e32 v59, v48
	v_mov_b32_e32 v60, v48
	v_mov_b32_e32 v61, v48
	v_mov_b32_e32 v62, v48
	v_mov_b32_e32 v63, v48
	s_add_u32 s38, s0, 0x14604000
	s_addc_u32 s39, s1, 0

; #define ATT_LOADK(t, r0, r1) do { r0 = *(const u32x4*)(kg0 + (size_t)(t) * 64 * DK); if (k1on) r1 = *(const u32x4*)(kg1 + (size_t)(t) * 64 * DK); } while (0)
; #define ATT_LOADV(t, r0, r1) do { if (von) { r0 = *(const u32x4*)(vg0 + (size_t)(t) * 64 * DV); r1 = *(const u32x4*)(vg0 + (size_t)(t) * 64 * DV + DV); } } while (0)
; template <int DK, int DV, int VAR>
; __device__ __forceinline__ void attn_pass(LAS unsigned char* lds, const bf16_t* Qg, const bf16_t* Kg, const bf16_t* Vg, int ntiles, float cs, f32x16 (&O)[DV / 32], float& lsum, int wv) {
;     ...
;         if (VAR != 1) { if (t + 1 < ntiles) { ATT_LOADK(t + 1, ka0, ka1); ATT_LOADV(t + 1, va0, va1); } }
.LBB0_930:
	s_or_b64 exec, exec, s[8:9]
	global_load_dwordx4 v[132:135], v174, s[0:1]
	s_and_saveexec_b64 s[8:9], s[2:3]
	s_cbranch_execz .LBB0_932
	global_load_dwordx4 v[124:127], v172, s[0:1]
.LBB0_932:
	s_or_b64 exec, exec, s[8:9]
	s_and_saveexec_b64 s[8:9], s[4:5]
	s_cbranch_execz .LBB0_934
	global_load_dwordx4 v[128:131], v170, s[38:39]
	global_load_dwordx4 v[120:123], v170, s[38:39] offset:128

.LBB0_954:
	s_or_b64 exec, exec, s[0:1]
	v_add_co_u32_e32 v0, vcc, 0x4000, v16
	v_mad_u32_u24 v33, v73, s9, 0
	s_nop 0
	v_addc_co_u32_e32 v1, vcc, 0, v17, vcc
	global_load_dwordx4 v[152:155], v[0:1], off
	global_load_dwordx4 v[156:159], v[0:1], off offset:256
	v_add_u32_e32 v242, v33, v204
	ds_read_b128 v[0:3], v242
	ds_read_b128 v[16:19], v242 offset:0x1200
	ds_read_b128 v[34:37], v242 offset:32
	ds_read_b128 v[38:41], v242 offset:0x1220
	ds_read_b128 v[42:45], v242 offset:64
	ds_read_b128 v[46:49], v242 offset:0x1240
	ds_read_b128 v[56:59], v242 offset:96
	ds_read_b128 v[50:53], v242 offset:0x1260
	s_waitcnt lgkmcnt(0)
	v_lshlrev_b32_e32 v244, 3, v32
	v_mfma_f32_32x32x16_bf16 v[0:15], v[0:3], v[140:143], 0
	v_lshlrev_b32_e32 v32, 3, v73
	v_sub_u32_e32 v32, v33, v32
	v_add_u32_e32 v243, v32, v244
	v_add_u32_e32 v72, 0x3400, v243
	v_and_b32_e32 v91, 15, v91
	v_mul_u32_u24_e32 v245, 0x90, v73
	v_mul_u32_u24_e32 v246, 0x88, v73
	v_mfma_f32_32x32x16_bf16 v[16:31], v[16:19], v[140:143], 0
	s_movk_i32 s1, 0xffe0
	s_and_b32 s0, s13, 28
	s_add_i32 s0, s8, s0
	s_mul_hi_i32 s9, s0, 0x90000
	s_mul_i32 s8, s0, 0x90000
	s_mov_b32 s28, 0x8000
	v_mfma_f32_32x32x16_bf16 v[0:15], v[34:37], v[136:139], v[0:15]
	v_mfma_f32_32x32x16_bf16 v[16:31], v[38:41], v[136:139], v[16:31]
	v_mfma_f32_32x32x16_bf16 v[0:15], v[42:45], v[132:135], v[0:15]
	v_mfma_f32_32x32x16_bf16 v[16:31], v[46:49], v[132:135], v[16:31]
	v_mfma_f32_32x32x16_bf16 v[16:31], v[50:53], v[128:131], v[16:31]
	ds_read_b64 v[94:95], v72
	ds_read_b64 v[96:97], v72 offset:16
	ds_read_b64 v[60:61], v72 offset:32
	ds_read_b64 v[62:63], v72 offset:48
	ds_read_b64 v[52:53], v72 offset:64
	ds_read_b64 v[54:55], v72 offset:80
	ds_read_b64 v[48:49], v72 offset:96
	ds_read_b64 v[50:51], v72 offset:112
	ds_read_b64 v[44:45], v72 offset:0x1100
	ds_read_b64 v[46:47], v72 offset:0x1110
	ds_read_b64 v[40:41], v72 offset:0x1120
	ds_read_b64 v[42:43], v72 offset:0x1130
	ds_read_b64 v[36:37], v72 offset:0x1140
	ds_read_b64 v[38:39], v72 offset:0x1150
	ds_read_b64 v[32:33], v72 offset:0x1160
	ds_read_b64 v[34:35], v72 offset:0x1170
	s_nop 0
	s_waitcnt lgkmcnt(0)
	v_mfma_f32_32x32x16_bf16 v[0:15], v[56:59], v[128:131], v[0:15]
	s_nop 11
	v_max_f32_e32 v57, v1, v17
	v_max_f32_e32 v58, v3, v19
	v_max_f32_e32 v56, v0, v16
	v_max3_f32 v58, v2, v18, v58
	v_max3_f32 v56, v56, v57, v58
	v_max_f32_e32 v57, v5, v21
	v_max_f32_e32 v58, v7, v23
	v_max3_f32 v57, v4, v20, v57
	v_max3_f32 v58, v6, v22, v58
	v_max3_f32 v56, v56, v57, v58
	v_max_f32_e32 v57, v9, v25
	v_max_f32_e32 v58, v11, v27
	v_max3_f32 v57, v8, v24, v57
	v_max3_f32 v58, v10, v26, v58
	v_max3_f32 v56, v56, v57, v58
	v_max_f32_e32 v57, v13, v29
	v_max_f32_e32 v59, v15, v15
	v_max_f32_e32 v58, v59, v31
	v_max3_f32 v57, v12, v28, v57
	v_max3_f32 v58, v14, v30, v58
	v_max3_f32 v56, v56, v57, v58
	v_mov_b32_e32 v57, v56
	s_nop 1
	v_permlane32_swap_b32_e32 v56, v57
	v_max_f32_e32 v72, v56, v57
	v_sub_f32_e32 v0, v0, v72
	v_sub_f32_e32 v1, v1, v72
	v_sub_f32_e32 v2, v2, v72
	v_sub_f32_e32 v3, v3, v72
	v_sub_f32_e32 v4, v4, v72
	v_sub_f32_e32 v5, v5, v72
	v_sub_f32_e32 v6, v6, v72
	v_sub_f32_e32 v7, v7, v72
	v_exp_f32_e32 v74, v0
	v_exp_f32_e32 v75, v1
	v_exp_f32_e32 v78, v2
	v_exp_f32_e32 v79, v3
	v_exp_f32_e32 v84, v4
	v_exp_f32_e32 v85, v5
	v_exp_f32_e32 v86, v6
	v_exp_f32_e32 v87, v7
	v_sub_f32_e32 v16, v16, v72
	v_sub_f32_e32 v17, v17, v72
	v_sub_f32_e32 v18, v18, v72
	v_sub_f32_e32 v19, v19, v72
	v_sub_f32_e32 v20, v20, v72
	v_sub_f32_e32 v21, v21, v72
	v_sub_f32_e32 v22, v22, v72
	v_sub_f32_e32 v23, v23, v72
	v_sub_f32_e32 v24, v24, v72
	v_sub_f32_e32 v25, v25, v72
	v_sub_f32_e32 v26, v26, v72
	v_sub_f32_e32 v27, v27, v72
	v_sub_f32_e32 v28, v28, v72
	v_sub_f32_e32 v29, v29, v72
	v_sub_f32_e32 v30, v30, v72
	v_sub_f32_e32 v31, v31, v72
	v_sub_f32_e32 v8, v8, v72
	v_sub_f32_e32 v9, v9, v72
	v_sub_f32_e32 v10, v10, v72
	v_sub_f32_e32 v11, v11, v72
	v_sub_f32_e32 v12, v12, v72
	v_cvt_pk_bf16_f32 v98, v74, v75
	v_cvt_pk_bf16_f32 v99, v78, v79
	v_cvt_pk_bf16_f32 v100, v84, v85
	v_cvt_pk_bf16_f32 v101, v86, v87
	v_sub_f32_e32 v56, v13, v72
	v_sub_f32_e32 v57, v14, v72
	v_sub_f32_e32 v58, v15, v72
	v_exp_f32_e32 v76, v16
	v_exp_f32_e32 v77, v17
	v_exp_f32_e32 v80, v18
	v_exp_f32_e32 v81, v19
	v_exp_f32_e32 v82, v20
	v_exp_f32_e32 v83, v21
	v_exp_f32_e32 v88, v22
	v_exp_f32_e32 v89, v23
	v_exp_f32_e32 v122, v8
	v_exp_f32_e32 v123, v9
	v_exp_f32_e32 v124, v24
	v_exp_f32_e32 v125, v25
	v_exp_f32_e32 v126, v10
	v_exp_f32_e32 v127, v11
	v_exp_f32_e32 v160, v12
	v_mfma_f32_32x32x16_bf16 v[0:15], v[94:97], v[98:101], 0
	v_exp_f32_e32 v164, v26
	v_exp_f32_e32 v165, v27
	v_exp_f32_e32 v166, v28
	v_exp_f32_e32 v167, v29
	v_exp_f32_e32 v168, v30
	v_exp_f32_e32 v169, v31
	v_exp_f32_e32 v161, v56
	v_mfma_f32_32x32x16_bf16 v[16:31], v[44:47], v[98:101], 0
	v_exp_f32_e32 v162, v57
	v_exp_f32_e32 v163, v58
	v_cvt_pk_bf16_f32 v94, v122, v123
	v_cvt_pk_bf16_f32 v95, v126, v127
	v_cvt_pk_bf16_f32 v96, v160, v161
	v_cvt_pk_bf16_f32 v97, v162, v163
	v_cvt_pk_bf16_f32 v102, v76, v77
	v_cvt_pk_bf16_f32 v103, v80, v81
	v_mfma_f32_32x32x16_bf16 v[0:15], v[60:63], v[94:97], v[0:15]
	v_cvt_pk_bf16_f32 v104, v82, v83
	v_cvt_pk_bf16_f32 v105, v88, v89
	v_cvt_pk_bf16_f32 v106, v124, v125
	v_cvt_pk_bf16_f32 v107, v164, v165
	v_cvt_pk_bf16_f32 v108, v166, v167
	v_cvt_pk_bf16_f32 v109, v168, v169
	v_pk_add_f32 v[74:75], v[74:75], 0 op_sel_hi:[1,0]
	v_mfma_f32_32x32x16_bf16 v[16:31], v[40:43], v[94:97], v[16:31]
	v_add_f32_e64 v74, v76, v74
	v_add_f32_e64 v75, v77, v75
	v_add_f32_e64 v74, v78, v74
	v_add_f32_e64 v75, v79, v75
	v_add_f32_e64 v74, v80, v74
	v_add_f32_e64 v75, v81, v75
; #define ATT_LOADK(t, r0, r1) do { r0 = *(const u32x4*)(kg0 + (size_t)(t) * 64 * DK); if (k1on) r1 = *(const u32x4*)(kg1 + (size_t)(t) * 64 * DK); } while (0)
; #define ATT_LOADV(t, r0, r1) do { if (von) { r0 = *(const u32x4*)(vg0 + (size_t)(t) * 64 * DV); r1 = *(const u32x4*)(vg0 + (size_t)(t) * 64 * DV + DV); } } while (0)
; #define ATT_STOREK(bi, r0, r1) do { LAS unsigned char* kb_ = lds + (bi) * ATT_BUF; *(LAS u32x4*)(kb_ + kl0) = r0; if (k1on) *(LAS u32x4*)(kb_ + kl1) = r1; } while (0)
; template <int DK, int DV, int VAR>
; __device__ __forceinline__ void attn_pass(LAS unsigned char* lds, const bf16_t* Qg, const bf16_t* Kg, const bf16_t* Vg, int ntiles, float cs, f32x16 (&O)[DV / 32], float& lsum, int wv) {
;     ...
; #pragma unroll
;     for (int t = 0; t < DV / 32; ++t)
; #pragma unroll
;         for (int i = 0; i < 16; ++i) O[t][i] = 0.f;
;     float mrun = 0.f, lrun = 0.f; (void)cs;
;     f32x16 Sa0, Sa1, negm;
; #pragma unroll
;     for (int i = 0; i < 16; ++i) negm[i] = 0.f;
;     __syncthreads();
;     ATT_LOADK(0, ka0, ka1); ATT_LOADV(0, va0, va1);
;     for (int t = 0; t < ntiles; ++t) {
;         if (VAR != 1 || t < 2) { ATT_STOREK(t & 1, ka0, ka1); ATT_STOREV(t & 1, va0, va1); }
;         __syncthreads();
;         if (VAR != 1) { if (t + 1 < ntiles) { ATT_LOADK(t + 1, ka0, ka1); ATT_LOADV(t + 1, va0, va1); } }
	v_pk_add_f32 v[74:75], v[84:85], v[74:75]
	v_mfma_f32_32x32x16_bf16 v[0:15], v[52:55], v[102:105], v[0:15]
	v_add_u32_e32 v52, 0x5600, v243
	v_add_f32_e64 v74, v82, v74
	v_add_f32_e64 v75, v83, v75
	v_add_f32_e64 v74, v86, v74
	v_add_f32_e64 v75, v87, v75
	v_pk_add_f32 v[74:75], v[88:89], v[74:75]
	v_mfma_f32_32x32x16_bf16 v[16:31], v[36:39], v[102:105], v[16:31]
	v_add_f32_e64 v74, v122, v74
	v_add_f32_e64 v75, v123, v75
	v_add_f32_e64 v74, v124, v74
	v_add_f32_e64 v75, v125, v75
	v_add_f32_e64 v74, v126, v74
	v_add_f32_e64 v75, v127, v75
	v_pk_add_f32 v[74:75], v[164:165], v[74:75]
	v_mfma_f32_32x32x16_bf16 v[0:15], v[48:51], v[106:109], v[0:15]
	v_add_f32_e64 v74, v160, v74
	v_add_f32_e64 v75, v161, v75
	v_add_f32_e64 v74, v166, v74
	v_add_f32_e64 v75, v167, v75
	v_add_f32_e64 v74, v162, v74
	v_add_f32_e64 v75, v163, v75
	v_pk_add_f32 v[74:75], v[168:169], v[74:75]
	v_mfma_f32_32x32x16_bf16 v[16:31], v[32:35], v[106:109], v[16:31]
	ds_read_b64 v[48:49], v52
	ds_read_b64 v[50:51], v52 offset:16
	ds_read_b64 v[44:45], v52 offset:32
	ds_read_b64 v[46:47], v52 offset:48
	ds_read_b64 v[40:41], v52 offset:64
	ds_read_b64 v[42:43], v52 offset:80
	ds_read_b64 v[36:37], v52 offset:96
	ds_read_b64 v[38:39], v52 offset:112
	ds_read_b64 v[32:33], v52 offset:0x1100
	ds_read_b64 v[34:35], v52 offset:0x1110
	ds_read_b64 v[118:119], v52 offset:0x1120
	ds_read_b64 v[120:121], v52 offset:0x1130
	ds_read_b64 v[114:115], v52 offset:0x1140
	ds_read_b64 v[116:117], v52 offset:0x1150
	ds_read_b64 v[110:111], v52 offset:0x1160
	ds_read_b64 v[112:113], v52 offset:0x1170
	v_pk_add_f32 v[74:75], v[74:75], v[74:75] op_sel_hi:[0,1]
	s_waitcnt lgkmcnt(0)
	v_mov_b32_e32 v73, v75
	v_pk_add_f32 v[212:213], v[72:73], 0 op_sel_hi:[1,0]
	v_lshlrev_b32_e32 v72, 1, v93
	v_lshlrev_b32_e32 v73, 1, v91
	v_mfma_f32_32x32x16_bf16 v[48:63], v[48:51], v[98:101], 0
	v_and_or_b32 v72, v72, s1, v73
	v_ashrrev_i32_e32 v73, 31, v72
	v_lshlrev_b64 v[72:73], 8, v[72:73]
	v_mov_b32_e32 v74, 0x90000
	v_mad_i64_i32 v[206:207], s[0:1], s0, v74, v[72:73]
	s_add_i32 s0, s20, s21
	v_mfma_f32_32x32x16_bf16 v[48:63], v[44:47], v[94:97], v[48:63]
	s_mul_i32 s21, s0, 0x48000
	s_mul_hi_i32 s20, s0, 0x48000
	s_add_u32 s0, s21, 0x9604000
	s_addc_u32 s1, s20, 0
	v_add_f32_e64 v80, -v212, neg(0)
	v_add_f32_e64 v81, -v213, neg(0)
	v_lshlrev_b32_e32 v72, 4, v92
	v_and_b32_e32 v73, 0xc0, v90
	v_mfma_f32_32x32x16_bf16 v[48:63], v[40:43], v[102:105], v[48:63]
	v_lshl_add_u64 v[68:69], v[68:69], 1, s[0:1]
	v_lshl_add_u64 v[64:65], v[64:65], 1, s[0:1]
	v_or3_b32 v206, v73, v72, v206
	v_lshl_add_u64 v[208:209], v[70:71], 1, v[68:69]
	v_lshl_add_u64 v[210:211], v[66:67], 1, v[64:65]
	v_mov_b32_e32 v81, v80
	v_mov_b32_e32 v82, v80
	v_mfma_f32_32x32x16_bf16 v[48:63], v[36:39], v[106:109], v[48:63]
	v_mov_b32_e32 v83, v80
	v_mov_b32_e32 v84, v80
	v_mov_b32_e32 v85, v80
	v_mov_b32_e32 v86, v80
	v_mov_b32_e32 v87, v80
	v_mov_b32_e32 v88, v80
	v_mov_b32_e32 v89, v80
	v_mfma_f32_32x32x16_bf16 v[32:47], v[32:35], v[98:101], 0
	v_mov_b32_e32 v90, v80
	v_mov_b32_e32 v91, v80
	v_mov_b32_e32 v92, v80
	v_mov_b32_e32 v93, v80
	v_mfma_f32_32x32x16_bf16 v[32:47], v[118:121], v[94:97], v[32:47]
	v_mov_b32_e32 v94, v80
	v_mov_b32_e32 v95, v80
	v_mfma_f32_32x32x16_bf16 v[32:47], v[114:117], v[102:105], v[32:47]
	v_mfma_f32_32x32x16_bf16 v[32:47], v[110:113], v[106:109], v[32:47]
	s_add_u32 s38, s4, 0xa808000
	s_addc_u32 s39, s5, 0
.LBB0_955:
	s_and_b32 s0, s28, 0x8000
	s_add_i32 s29, s0, 0
	v_add3_u32 v64, s29, v205, v220
	s_waitcnt vmcnt(2)
	ds_write_b128 v64, v[148:151]
	s_and_saveexec_b64 s[0:1], s[2:3]
	v_add3_u32 v64, s29, v219, v221
	ds_write_b128 v64, v[144:147]
	s_or_b64 exec, exec, s[0:1]
	v_add3_u32 v64, s29, v240, v241
	s_waitcnt vmcnt(0)
	v_perm_b32 v65, v156, v152, s85
	v_perm_b32 v66, v156, v152, s86
	v_add_u32_e32 v64, 0x3400, v64
	ds_write2_b32 v64, v65, v66 offset1:34
	v_perm_b32 v65, v157, v153, s85
	v_perm_b32 v66, v157, v153, s86
	ds_write2_b32 v64, v65, v66 offset0:68 offset1:102
	v_perm_b32 v65, v158, v154, s85
	v_perm_b32 v66, v158, v154, s86
	ds_write2_b32 v64, v65, v66 offset0:136 offset1:170
	v_perm_b32 v65, v159, v155, s85
	v_perm_b32 v66, v159, v155, s86
	ds_write2_b32 v64, v65, v66 offset0:204 offset1:238
	global_load_dwordx4 v[148:151], v210, s[4:5]
	s_and_saveexec_b64 s[0:1], s[2:3]
	s_cbranch_execz .LBB0_959
	global_load_dwordx4 v[144:147], v208, s[4:5]
.LBB0_959:
	s_or_b64 exec, exec, s[0:1]
	v_add3_u32 v96, s29, v245, v204
	global_load_dwordx4 v[152:155], v206, s[38:39]
	global_load_dwordx4 v[156:159], v206, s[38:39] offset:256
	s_waitcnt lgkmcnt(0)
	s_barrier
	ds_read_b128 v[64:67], v96
	ds_read_b128 v[68:71], v96 offset:0x1200
	ds_read_b128 v[72:75], v96 offset:32
	ds_read_b128 v[76:79], v96 offset:0x1220
	ds_read_b128 v[160:163], v96 offset:64
	ds_read_b128 v[164:167], v96 offset:0x1240
	ds_read_b128 v[168:171], v96 offset:96
	ds_read_b128 v[172:175], v96 offset:0x1260
	s_nop 0
	s_waitcnt lgkmcnt(7)
	v_mfma_f32_32x32x16_bf16 v[112:127], v[64:67], v[140:143], v[80:95]
	v_add_u32_e32 v64, s29, v246
	v_add3_u32 v247, v64, v244, s87
	s_waitcnt lgkmcnt(6)
	v_mfma_f32_32x32x16_bf16 v[96:111], v[68:71], v[140:143], v[80:95]
	s_waitcnt lgkmcnt(5)
	v_mfma_f32_32x32x16_bf16 v[112:127], v[72:75], v[136:139], v[112:127]
	s_waitcnt lgkmcnt(4)
	v_mfma_f32_32x32x16_bf16 v[96:111], v[76:79], v[136:139], v[96:111]
	s_waitcnt lgkmcnt(3)
	v_mfma_f32_32x32x16_bf16 v[112:127], v[160:163], v[132:135], v[112:127]
	s_waitcnt lgkmcnt(2)
	v_mfma_f32_32x32x16_bf16 v[96:111], v[164:167], v[132:135], v[96:111]
	s_waitcnt lgkmcnt(1)
	v_mfma_f32_32x32x16_bf16 v[112:127], v[168:171], v[128:131], v[112:127]
	s_waitcnt lgkmcnt(0)
	v_mfma_f32_32x32x16_bf16 v[96:111], v[172:175], v[128:131], v[96:111]
	ds_read_b64 v[188:189], v247
	ds_read_b64 v[190:191], v247 offset:16
	ds_read_b64 v[184:185], v247 offset:32
	ds_read_b64 v[186:187], v247 offset:48
	ds_read_b64 v[180:181], v247 offset:64
	ds_read_b64 v[182:183], v247 offset:80
	ds_read_b64 v[176:177], v247 offset:96
	ds_read_b64 v[178:179], v247 offset:112
	ds_read_b64 v[172:173], v247 offset:0x1100
	ds_read_b64 v[174:175], v247 offset:0x1110
	ds_read_b64 v[168:169], v247 offset:0x1120
	ds_read_b64 v[170:171], v247 offset:0x1130
	ds_read_b64 v[164:165], v247 offset:0x1140
	ds_read_b64 v[166:167], v247 offset:0x1150
	ds_read_b64 v[160:161], v247 offset:0x1160
	ds_read_b64 v[162:163], v247 offset:0x1170
	v_max3_f32 v65, v112, v113, v114
	v_max3_f32 v65, v65, v115, v116
	v_max3_f32 v65, v65, v117, v118
	v_max3_f32 v65, v65, v119, v120
	v_max3_f32 v65, v65, v121, v122
	v_max3_f32 v65, v65, v123, v124
	v_max3_f32 v65, v65, v125, v126
	v_max_f32_e32 v65, v65, v127
	v_max3_f32 v64, v96, v97, v98
	v_max3_f32 v66, v99, v100, v101
	v_max3_f32 v64, v64, v102, v103
	v_max3_f32 v66, v66, v104, v105
	v_max3_f32 v64, v64, v106, v107
	v_max3_f32 v66, v66, v108, v109
	v_max3_f32 v64, v64, v110, v111
	v_max3_f32 v64, v64, v66, v65
	v_mov_b32_e32 v65, v64
	s_nop 1
	v_permlane32_swap_b32_e32 v64, v65
	v_max_f32_e32 v64, v64, v65
	v_cmp_lt_f32_e32 vcc, s80, v64
	s_cbranch_vccz .LBB0_961
	v_max_f32_e32 v80, 0, v64
	v_exp_f32_e64 v64, -v80
	s_nop 0
	v_mov_b32_e32 v81, v64
	v_pk_mul_f32 v[14:15], v[14:15], v[64:65] op_sel_hi:[1,0]
	v_pk_mul_f32 v[12:13], v[12:13], v[64:65] op_sel_hi:[1,0]
	v_pk_mul_f32 v[10:11], v[10:11], v[64:65] op_sel_hi:[1,0]
	v_pk_mul_f32 v[8:9], v[8:9], v[64:65] op_sel_hi:[1,0]
	v_pk_mul_f32 v[6:7], v[6:7], v[64:65] op_sel_hi:[1,0]
	v_pk_mul_f32 v[4:5], v[4:5], v[64:65] op_sel_hi:[1,0]
	v_pk_mul_f32 v[2:3], v[2:3], v[64:65] op_sel_hi:[1,0]
	v_pk_mul_f32 v[0:1], v[0:1], v[64:65] op_sel_hi:[1,0]
	v_pk_mul_f32 v[30:31], v[30:31], v[64:65] op_sel_hi:[1,0]
	v_pk_mul_f32 v[28:29], v[28:29], v[64:65] op_sel_hi:[1,0]
	v_pk_mul_f32 v[26:27], v[26:27], v[64:65] op_sel_hi:[1,0]
	v_pk_mul_f32 v[24:25], v[24:25], v[64:65] op_sel_hi:[1,0]
	v_pk_mul_f32 v[22:23], v[22:23], v[64:65] op_sel_hi:[1,0]
	v_pk_mul_f32 v[20:21], v[20:21], v[64:65] op_sel_hi:[1,0]
	v_pk_mul_f32 v[18:19], v[18:19], v[64:65] op_sel_hi:[1,0]
	v_pk_mul_f32 v[16:17], v[16:17], v[64:65] op_sel_hi:[1,0]
	v_pk_mul_f32 v[62:63], v[62:63], v[64:65] op_sel_hi:[1,0]
	v_pk_mul_f32 v[60:61], v[60:61], v[64:65] op_sel_hi:[1,0]
	v_pk_mul_f32 v[58:59], v[58:59], v[64:65] op_sel_hi:[1,0]
	v_pk_mul_f32 v[56:57], v[56:57], v[64:65] op_sel_hi:[1,0]
	v_pk_mul_f32 v[54:55], v[54:55], v[64:65] op_sel_hi:[1,0]
	v_pk_mul_f32 v[52:53], v[52:53], v[64:65] op_sel_hi:[1,0]
	v_pk_mul_f32 v[50:51], v[50:51], v[64:65] op_sel_hi:[1,0]
	v_pk_mul_f32 v[48:49], v[48:49], v[64:65] op_sel_hi:[1,0]
	v_pk_mul_f32 v[46:47], v[46:47], v[64:65] op_sel_hi:[1,0]
	v_pk_mul_f32 v[44:45], v[44:45], v[64:65] op_sel_hi:[1,0]
	v_pk_mul_f32 v[42:43], v[42:43], v[64:65] op_sel_hi:[1,0]
	v_pk_mul_f32 v[40:41], v[40:41], v[64:65] op_sel_hi:[1,0]
	v_pk_mul_f32 v[38:39], v[38:39], v[64:65] op_sel_hi:[1,0]
	v_pk_mul_f32 v[36:37], v[36:37], v[64:65] op_sel_hi:[1,0]
	v_pk_mul_f32 v[34:35], v[34:35], v[64:65] op_sel_hi:[1,0]
	v_pk_mul_f32 v[32:33], v[32:33], v[64:65] op_sel_hi:[1,0]
	v_pk_add_f32 v[214:215], v[212:213], v[80:81]
	v_pk_mul_f32 v[64:65], v[212:213], v[80:81]
	v_pk_add_f32 v[112:113], v[112:113], v[80:81] op_sel_hi:[1,0] neg_lo:[0,1] neg_hi:[0,1]
	v_mov_b32_e32 v215, v65
	v_pk_add_f32 v[64:65], v[214:215], 0 neg_lo:[1,1] neg_hi:[1,1]
	v_pk_add_f32 v[96:97], v[96:97], v[80:81] op_sel_hi:[1,0] neg_lo:[0,1] neg_hi:[0,1]
	v_pk_add_f32 v[114:115], v[114:115], v[80:81] op_sel_hi:[1,0] neg_lo:[0,1] neg_hi:[0,1]
	v_pk_add_f32 v[98:99], v[98:99], v[80:81] op_sel_hi:[1,0] neg_lo:[0,1] neg_hi:[0,1]
	v_pk_add_f32 v[116:117], v[116:117], v[80:81] op_sel_hi:[1,0] neg_lo:[0,1] neg_hi:[0,1]
	v_pk_add_f32 v[100:101], v[100:101], v[80:81] op_sel_hi:[1,0] neg_lo:[0,1] neg_hi:[0,1]
	v_pk_add_f32 v[118:119], v[118:119], v[80:81] op_sel_hi:[1,0] neg_lo:[0,1] neg_hi:[0,1]
	v_pk_add_f32 v[102:103], v[102:103], v[80:81] op_sel_hi:[1,0] neg_lo:[0,1] neg_hi:[0,1]
	v_pk_add_f32 v[120:121], v[120:121], v[80:81] op_sel_hi:[1,0] neg_lo:[0,1] neg_hi:[0,1]
	v_pk_add_f32 v[104:105], v[104:105], v[80:81] op_sel_hi:[1,0] neg_lo:[0,1] neg_hi:[0,1]
	v_pk_add_f32 v[122:123], v[122:123], v[80:81] op_sel_hi:[1,0] neg_lo:[0,1] neg_hi:[0,1]
	v_pk_add_f32 v[106:107], v[106:107], v[80:81] op_sel_hi:[1,0] neg_lo:[0,1] neg_hi:[0,1]
	v_pk_add_f32 v[124:125], v[124:125], v[80:81] op_sel_hi:[1,0] neg_lo:[0,1] neg_hi:[0,1]
	v_pk_add_f32 v[108:109], v[108:109], v[80:81] op_sel_hi:[1,0] neg_lo:[0,1] neg_hi:[0,1]
	v_mov_b32_e32 v65, v64
	v_mov_b32_e32 v66, v64
	v_mov_b32_e32 v67, v64
	v_mov_b32_e32 v68, v64
	v_mov_b32_e32 v69, v64
	v_mov_b32_e32 v70, v64
	v_mov_b32_e32 v71, v64
	v_mov_b32_e32 v72, v64
	v_mov_b32_e32 v73, v64
	v_mov_b32_e32 v74, v64
	v_mov_b32_e32 v75, v64
	v_mov_b32_e32 v76, v64
	v_mov_b32_e32 v77, v64
	v_mov_b32_e32 v78, v64
	v_mov_b32_e32 v79, v64
	v_pk_add_f32 v[126:127], v[126:127], v[80:81] op_sel_hi:[1,0] neg_lo:[0,1] neg_hi:[0,1]
	v_pk_add_f32 v[110:111], v[110:111], v[80:81] op_sel_hi:[1,0] neg_lo:[0,1] neg_hi:[0,1]
	v_mov_b32_e32 v80, v64
	v_mov_b32_e32 v81, v64
	v_mov_b32_e32 v82, v64
	v_mov_b32_e32 v83, v64
	v_mov_b32_e32 v84, v64
	v_mov_b32_e32 v85, v64
	v_mov_b32_e32 v86, v64
	v_mov_b32_e32 v87, v64
	v_mov_b32_e32 v88, v64
	v_mov_b32_e32 v89, v64
	v_mov_b32_e32 v90, v64
	v_mov_b32_e32 v91, v64
	v_mov_b32_e32 v92, v64
	v_mov_b32_e32 v93, v64
	v_mov_b32_e32 v94, v64
	v_mov_b32_e32 v95, v64
	v_mov_b32_e32 v212, v214
	s_branch .LBB0_962

.LBB0_974:
	s_or_b64 exec, exec, s[0:1]
	v_add_co_u32_e32 v0, vcc, 0x4000, v16
	v_mad_u32_u24 v33, v32, s22, 0
	s_nop 0
	v_addc_co_u32_e32 v1, vcc, 0, v17, vcc
	v_lshlrev_b32_e32 v244, 3, v19
	v_and_b32_e32 v91, 15, v18
	global_load_dwordx4 v[152:155], v[0:1], off
	global_load_dwordx4 v[156:159], v[0:1], off offset:256
	v_add_u32_e32 v245, v33, v192
	ds_read_b128 v[0:3], v245
	ds_read_b128 v[16:19], v245 offset:0x1200
	ds_read_b128 v[34:37], v245 offset:32
	ds_read_b128 v[38:41], v245 offset:0x1220
	ds_read_b128 v[42:45], v245 offset:64
	ds_read_b128 v[46:49], v245 offset:0x1240
	ds_read_b128 v[50:53], v245 offset:96
	ds_read_b128 v[54:57], v245 offset:0x1260
	v_mul_u32_u24_e32 v246, 0x90, v32
	s_waitcnt lgkmcnt(7)
	v_mfma_f32_32x32x16_bf16 v[0:15], v[0:3], v[140:143], 0
	v_mul_u32_u24_e32 v247, 0x88, v32
	v_lshlrev_b32_e32 v32, 3, v32
	v_sub_u32_e32 v32, v33, v32
	v_add_u32_e32 v248, v32, v244
	v_add_u32_e32 v64, 0x3400, v248
	s_movk_i32 s0, 0xffe0
	s_waitcnt lgkmcnt(6)
	v_mfma_f32_32x32x16_bf16 v[16:31], v[16:19], v[140:143], 0
	s_waitcnt lgkmcnt(5)
	v_mfma_f32_32x32x16_bf16 v[0:15], v[34:37], v[136:139], v[0:15]
	s_waitcnt lgkmcnt(4)
	v_mfma_f32_32x32x16_bf16 v[16:31], v[38:41], v[136:139], v[16:31]
	s_waitcnt lgkmcnt(3)
	v_mfma_f32_32x32x16_bf16 v[0:15], v[42:45], v[132:135], v[0:15]
	s_waitcnt lgkmcnt(2)
	v_mfma_f32_32x32x16_bf16 v[16:31], v[46:49], v[132:135], v[16:31]
	s_waitcnt lgkmcnt(1)
	v_mfma_f32_32x32x16_bf16 v[0:15], v[50:53], v[128:131], v[0:15]
	s_waitcnt lgkmcnt(0)
	v_mfma_f32_32x32x16_bf16 v[16:31], v[54:57], v[128:131], v[16:31]
	ds_read_b64 v[60:61], v64
	ds_read_b64 v[62:63], v64 offset:16
	ds_read_b64 v[56:57], v64 offset:32
	ds_read_b64 v[58:59], v64 offset:48
	ds_read_b64 v[52:53], v64 offset:64
	ds_read_b64 v[54:55], v64 offset:80
	ds_read_b64 v[48:49], v64 offset:96
	ds_read_b64 v[50:51], v64 offset:112
	ds_read_b64 v[44:45], v64 offset:0x1100
	ds_read_b64 v[46:47], v64 offset:0x1110
	ds_read_b64 v[40:41], v64 offset:0x1120
	ds_read_b64 v[42:43], v64 offset:0x1130
	ds_read_b64 v[36:37], v64 offset:0x1140
	ds_read_b64 v[38:39], v64 offset:0x1150
	ds_read_b64 v[32:33], v64 offset:0x1160
	ds_read_b64 v[34:35], v64 offset:0x1170
	s_nop 10
	v_max_f32_e32 v64, v0, v16
	v_max_f32_e32 v65, v1, v17
	v_max_f32_e32 v66, v3, v19
	v_max3_f32 v66, v2, v18, v66
	v_max3_f32 v64, v64, v65, v66
	v_max_f32_e32 v65, v5, v21
	v_max_f32_e32 v66, v7, v23
	v_max3_f32 v65, v4, v20, v65
	v_max3_f32 v66, v6, v22, v66
	v_max3_f32 v64, v64, v65, v66
	v_max_f32_e32 v65, v9, v25
	v_max_f32_e32 v66, v11, v27
	v_max3_f32 v65, v8, v24, v65
	v_max3_f32 v66, v10, v26, v66
	v_max3_f32 v64, v64, v65, v66
	v_max_f32_e32 v65, v13, v29
	v_max_f32_e32 v66, v15, v31
	v_max3_f32 v65, v12, v28, v65
	v_max3_f32 v66, v14, v30, v66
	v_max3_f32 v64, v64, v65, v66
	v_mov_b32_e32 v65, v64
	s_nop 1
	v_permlane32_swap_b32_e32 v64, v65
	v_max_f32_e32 v80, v64, v65
	v_sub_f32_e32 v0, v0, v80
	v_sub_f32_e32 v1, v1, v80
	v_sub_f32_e32 v16, v16, v80
	v_sub_f32_e32 v17, v17, v80
	v_exp_f32_e32 v0, v0
	v_exp_f32_e32 v1, v1
	v_sub_f32_e32 v64, v26, v80
	v_sub_f32_e32 v65, v27, v80
	v_sub_f32_e32 v26, v2, v80
	v_sub_f32_e32 v27, v3, v80
	v_exp_f32_e32 v2, v16
	v_exp_f32_e32 v3, v17
	v_sub_f32_e32 v18, v18, v80
	v_sub_f32_e32 v19, v19, v80
	v_sub_f32_e32 v68, v30, v80
	v_sub_f32_e32 v69, v31, v80
	v_sub_f32_e32 v30, v6, v80
	v_sub_f32_e32 v31, v7, v80
	v_exp_f32_e32 v6, v26
	v_exp_f32_e32 v7, v27
	v_sub_f32_e32 v66, v28, v80
	v_sub_f32_e32 v67, v29, v80
	v_sub_f32_e32 v28, v4, v80
	v_sub_f32_e32 v29, v5, v80
	v_sub_f32_e32 v70, v8, v80
	v_sub_f32_e32 v71, v9, v80
	v_exp_f32_e32 v8, v18
	v_exp_f32_e32 v9, v19
	v_sub_f32_e32 v20, v20, v80
	v_sub_f32_e32 v21, v21, v80
	v_sub_f32_e32 v72, v10, v80
	v_sub_f32_e32 v73, v11, v80
	v_pk_add_f32 v[4:5], v[0:1], 0 op_sel_hi:[1,0]
	v_exp_f32_e32 v10, v28
	v_exp_f32_e32 v11, v29
	v_sub_f32_e32 v74, v12, v80
	v_sub_f32_e32 v75, v13, v80
	v_pk_add_f32 v[4:5], v[2:3], v[4:5]
	v_exp_f32_e32 v12, v20
	v_exp_f32_e32 v13, v21
	v_sub_f32_e32 v22, v22, v80
	v_sub_f32_e32 v23, v23, v80
	v_sub_f32_e32 v81, v14, v80
	v_sub_f32_e32 v86, v15, v80
	v_pk_add_f32 v[4:5], v[6:7], v[4:5]
	v_exp_f32_e32 v14, v30
	v_exp_f32_e32 v15, v31
	v_pk_add_f32 v[4:5], v[8:9], v[4:5]
	v_exp_f32_e32 v20, v22
	v_exp_f32_e32 v21, v23
	v_sub_f32_e32 v24, v24, v80
	v_sub_f32_e32 v25, v25, v80
	v_pk_add_f32 v[4:5], v[10:11], v[4:5]
	v_exp_f32_e32 v22, v70
	v_exp_f32_e32 v23, v71
	v_pk_add_f32 v[4:5], v[12:13], v[4:5]
	v_exp_f32_e32 v24, v24
	v_exp_f32_e32 v25, v25
	v_pk_add_f32 v[4:5], v[14:15], v[4:5]
	v_exp_f32_e32 v26, v72
	v_exp_f32_e32 v27, v73
	v_pk_add_f32 v[4:5], v[20:21], v[4:5]
	v_exp_f32_e32 v28, v64
	v_exp_f32_e32 v29, v65
	v_pk_add_f32 v[4:5], v[22:23], v[4:5]
	v_exp_f32_e32 v30, v74
	v_exp_f32_e32 v31, v75
	v_pk_add_f32 v[4:5], v[24:25], v[4:5]
	v_exp_f32_e32 v70, v66
	v_exp_f32_e32 v71, v67
	v_pk_add_f32 v[4:5], v[26:27], v[4:5]
	v_exp_f32_e32 v64, v81
	v_exp_f32_e32 v65, v86
	v_pk_add_f32 v[4:5], v[28:29], v[4:5]
	v_exp_f32_e32 v92, v68
	v_exp_f32_e32 v93, v69
	v_pk_add_f32 v[4:5], v[30:31], v[4:5]
	v_cvt_pk_bf16_f32 v16, v0, v1
	v_pk_add_f32 v[4:5], v[70:71], v[4:5]
	v_cvt_pk_bf16_f32 v17, v6, v7
	v_pk_add_f32 v[4:5], v[64:65], v[4:5]
	v_cvt_pk_bf16_f32 v18, v10, v11
	v_pk_add_f32 v[4:5], v[92:93], v[4:5]
	v_cvt_pk_bf16_f32 v19, v14, v15
	v_pk_add_f32 v[86:87], v[4:5], v[4:5] op_sel_hi:[0,1]
	v_cvt_pk_bf16_f32 v75, v64, v65
	v_cvt_pk_bf16_f32 v64, v2, v3
	v_cvt_pk_bf16_f32 v65, v8, v9
	v_cvt_pk_bf16_f32 v66, v12, v13
	s_waitcnt lgkmcnt(14)
; #define ATT_LOADK(t, r0, r1) do { r0 = *(const u32x4*)(kg0 + (size_t)(t) * 64 * DK); if (k1on) r1 = *(const u32x4*)(kg1 + (size_t)(t) * 64 * DK); } while (0)
; #define ATT_LOADV(t, r0, r1) do { if (von) { r0 = *(const u32x4*)(vg0 + (size_t)(t) * 64 * DV); r1 = *(const u32x4*)(vg0 + (size_t)(t) * 64 * DV + DV); } } while (0)
; #define ATT_STOREK(bi, r0, r1) do { LAS unsigned char* kb_ = lds + (bi) * ATT_BUF; *(LAS u32x4*)(kb_ + kl0) = r0; if (k1on) *(LAS u32x4*)(kb_ + kl1) = r1; } while (0)
; template <int DK, int DV, int VAR>
; __device__ __forceinline__ void attn_pass(LAS unsigned char* lds, const bf16_t* Qg, const bf16_t* Kg, const bf16_t* Vg, int ntiles, float cs, f32x16 (&O)[DV / 32], float& lsum, int wv) {
;     ...
; #pragma unroll
;     for (int t = 0; t < DV / 32; ++t)
; #pragma unroll
;         for (int i = 0; i < 16; ++i) O[t][i] = 0.f;
;     float mrun = 0.f, lrun = 0.f; (void)cs;
;     f32x16 Sa0, Sa1, negm;
; #pragma unroll
;     for (int i = 0; i < 16; ++i) negm[i] = 0.f;
;     __syncthreads();
;     ATT_LOADK(0, ka0, ka1); ATT_LOADV(0, va0, va1);
;     for (int t = 0; t < ntiles; ++t) {
;         if (VAR != 1 || t < 2) { ATT_STOREK(t & 1, ka0, ka1); ATT_STOREV(t & 1, va0, va1); }
;         __syncthreads();
;         if (VAR != 1) { if (t + 1 < ntiles) { ATT_LOADK(t + 1, ka0, ka1); ATT_LOADV(t + 1, va0, va1); } }
	v_mfma_f32_32x32x16_bf16 v[0:15], v[60:63], v[16:19], 0
	v_cvt_pk_bf16_f32 v72, v22, v23
	v_cvt_pk_bf16_f32 v73, v26, v27
	v_cvt_pk_bf16_f32 v74, v30, v31
	v_cvt_pk_bf16_f32 v67, v20, v21
	v_cvt_pk_bf16_f32 v68, v24, v25
	v_cvt_pk_bf16_f32 v69, v28, v29
	v_cvt_pk_bf16_f32 v70, v70, v71
	s_waitcnt lgkmcnt(12)
	v_mfma_f32_32x32x16_bf16 v[0:15], v[56:59], v[72:75], v[0:15]
	v_cvt_pk_bf16_f32 v71, v92, v93
	v_mov_b32_e32 v81, v87
	v_add_f32_e64 v210, v80, 0
	v_add_f32_e64 v211, v81, 0
	v_add_f32_e64 v80, -v210, neg(0)
	v_add_f32_e64 v81, -v211, neg(0)
	v_mov_b32_e32 v81, v80
	s_waitcnt lgkmcnt(10)
	v_mfma_f32_32x32x16_bf16 v[0:15], v[52:55], v[64:67], v[0:15]
	v_mov_b32_e32 v86, v80
	v_mov_b32_e32 v87, v80
	s_waitcnt lgkmcnt(8)
	v_mfma_f32_32x32x16_bf16 v[0:15], v[48:51], v[68:71], v[0:15]
	s_waitcnt lgkmcnt(6)
	v_mfma_f32_32x32x16_bf16 v[48:63], v[44:47], v[16:19], 0
	s_waitcnt lgkmcnt(4)
	v_mfma_f32_32x32x16_bf16 v[48:63], v[40:43], v[72:75], v[48:63]
	s_waitcnt lgkmcnt(2)
	v_mfma_f32_32x32x16_bf16 v[48:63], v[36:39], v[64:67], v[48:63]
	v_add_u32_e32 v36, 0x5600, v248
	s_waitcnt lgkmcnt(0)
	v_mfma_f32_32x32x16_bf16 v[48:63], v[32:35], v[68:71], v[48:63]
	ds_read_b64 v[32:33], v36
	ds_read_b64 v[34:35], v36 offset:16
	ds_read_b64 v[104:105], v36 offset:32
	ds_read_b64 v[106:107], v36 offset:48
	ds_read_b64 v[28:29], v36 offset:64
	ds_read_b64 v[30:31], v36 offset:80
	ds_read_b64 v[24:25], v36 offset:96
	ds_read_b64 v[26:27], v36 offset:112
	ds_read_b64 v[20:21], v36 offset:0x1100
	ds_read_b64 v[22:23], v36 offset:0x1110
	ds_read_b64 v[100:101], v36 offset:0x1120
	ds_read_b64 v[102:103], v36 offset:0x1130
	ds_read_b64 v[96:97], v36 offset:0x1140
	ds_read_b64 v[98:99], v36 offset:0x1150
	ds_read_b64 v[92:93], v36 offset:0x1160
	ds_read_b64 v[94:95], v36 offset:0x1170
	s_nop 0
	s_nop 0
	s_waitcnt lgkmcnt(14)
	v_mfma_f32_32x32x16_bf16 v[32:47], v[32:35], v[16:19], 0
	s_waitcnt lgkmcnt(12)
	v_mfma_f32_32x32x16_bf16 v[32:47], v[104:107], v[72:75], v[32:47]
	s_waitcnt lgkmcnt(10)
	v_mfma_f32_32x32x16_bf16 v[32:47], v[28:31], v[64:67], v[32:47]
	s_waitcnt lgkmcnt(8)
	v_mfma_f32_32x32x16_bf16 v[32:47], v[24:27], v[68:71], v[32:47]
	s_waitcnt lgkmcnt(6)
	v_mfma_f32_32x32x16_bf16 v[16:31], v[20:23], v[16:19], 0
	s_waitcnt lgkmcnt(4)
	v_mfma_f32_32x32x16_bf16 v[16:31], v[100:103], v[72:75], v[16:31]
	s_waitcnt lgkmcnt(2)
	v_mfma_f32_32x32x16_bf16 v[16:31], v[96:99], v[64:67], v[16:31]
	v_lshlrev_b32_e32 v64, 1, v90
	v_lshlrev_b32_e32 v65, 1, v91
	v_and_or_b32 v64, v64, s0, v65
	v_ashrrev_i32_e32 v65, 31, v64
	v_lshlrev_b64 v[64:65], 8, v[64:65]
	v_lshlrev_b32_e32 v66, 4, v89
	s_add_u32 s0, s21, 0x964c000
	s_waitcnt lgkmcnt(0)
	v_mfma_f32_32x32x16_bf16 v[16:31], v[92:95], v[68:71], v[16:31]
	v_lshl_add_u64 v[64:65], s[8:9], 0, v[64:65]
	v_and_or_b32 v66, v88, s69, v66
	v_mov_b32_e32 v67, v193
	s_addc_u32 s1, s20, 0
	v_lshl_add_u64 v[204:205], v[64:65], 0, v[66:67]
	v_lshl_add_u64 v[64:65], v[82:83], 1, s[0:1]
	v_lshl_add_u64 v[206:207], v[84:85], 1, v[64:65]
	v_lshl_add_u64 v[64:65], v[76:77], 1, s[0:1]
	v_lshl_add_u64 v[208:209], v[78:79], 1, v[64:65]
	s_mov_b32 s8, 0x8000
	v_mov_b32_e32 v82, v80
	v_mov_b32_e32 v83, v80
	v_mov_b32_e32 v84, v80
	v_mov_b32_e32 v85, v80
	v_mov_b32_e32 v88, v80
	v_mov_b32_e32 v89, v80
	v_mov_b32_e32 v90, v80
	v_mov_b32_e32 v91, v80
	v_mov_b32_e32 v92, v80
	v_mov_b32_e32 v93, v80
	v_mov_b32_e32 v94, v80
	v_mov_b32_e32 v95, v80
	s_add_u32 s38, s4, 0xa808000
	s_addc_u32 s39, s5, 0
.LBB0_975:
	s_and_b32 s0, s8, 0x8000
	s_add_i32 s9, s0, 0
	v_add3_u32 v64, s9, v220, v222
	s_waitcnt vmcnt(2)
	ds_write_b128 v64, v[148:151]
	s_and_saveexec_b64 s[0:1], s[2:3]
	v_add3_u32 v64, s9, v221, v223
	ds_write_b128 v64, v[144:147]
	s_or_b64 exec, exec, s[0:1]
	v_add3_u32 v64, s9, v242, v243
	s_waitcnt vmcnt(0)
	v_perm_b32 v65, v156, v152, s85
	v_perm_b32 v66, v156, v152, s86
	v_add_u32_e32 v64, 0x3400, v64
	ds_write2_b32 v64, v65, v66 offset1:34
	v_perm_b32 v65, v157, v153, s85
	v_perm_b32 v66, v157, v153, s86
	ds_write2_b32 v64, v65, v66 offset0:68 offset1:102
	v_perm_b32 v65, v158, v154, s85
	v_perm_b32 v66, v158, v154, s86
	ds_write2_b32 v64, v65, v66 offset0:136 offset1:170
	v_perm_b32 v65, v159, v155, s85
	v_perm_b32 v66, v159, v155, s86
	ds_write2_b32 v64, v65, v66 offset0:204 offset1:238
	global_load_dwordx4 v[148:151], v208, s[4:5]
	s_and_saveexec_b64 s[0:1], s[2:3]
	s_cbranch_execz .LBB0_979
	global_load_dwordx4 v[144:147], v206, s[4:5]
.LBB0_979:
	s_or_b64 exec, exec, s[0:1]
	v_add3_u32 v96, s9, v246, v192
	global_load_dwordx4 v[152:155], v204, s[38:39]
	global_load_dwordx4 v[156:159], v204, s[38:39] offset:256
	s_waitcnt lgkmcnt(0)
	s_barrier
	ds_read_b128 v[64:67], v96
	ds_read_b128 v[68:71], v96 offset:0x1200
	ds_read_b128 v[72:75], v96 offset:32
	ds_read_b128 v[76:79], v96 offset:0x1220
	ds_read_b128 v[160:163], v96 offset:64
	ds_read_b128 v[164:167], v96 offset:0x1240
	ds_read_b128 v[168:171], v96 offset:96
	ds_read_b128 v[172:175], v96 offset:0x1260
	v_mov_b32_e32 v254, 0xc00
	s_waitcnt lgkmcnt(7)
	v_mfma_f32_32x32x16_bf16 v[112:127], v[64:67], v[140:143], v[80:95]
	v_add_u32_e32 v64, s9, v247
	v_add3_u32 v249, v64, v244, s87
	s_waitcnt lgkmcnt(6)
	v_mfma_f32_32x32x16_bf16 v[96:111], v[68:71], v[140:143], v[80:95]
	s_waitcnt lgkmcnt(5)
	v_mfma_f32_32x32x16_bf16 v[112:127], v[72:75], v[136:139], v[112:127]
	s_waitcnt lgkmcnt(4)
	v_mfma_f32_32x32x16_bf16 v[96:111], v[76:79], v[136:139], v[96:111]
	s_waitcnt lgkmcnt(3)
	v_mfma_f32_32x32x16_bf16 v[112:127], v[160:163], v[132:135], v[112:127]
	s_waitcnt lgkmcnt(2)
	v_mfma_f32_32x32x16_bf16 v[96:111], v[164:167], v[132:135], v[96:111]
	s_waitcnt lgkmcnt(1)
	v_mfma_f32_32x32x16_bf16 v[112:127], v[168:171], v[128:131], v[112:127]
	s_waitcnt lgkmcnt(0)
	v_mfma_f32_32x32x16_bf16 v[96:111], v[172:175], v[128:131], v[96:111]
	ds_read_b64 v[188:189], v249
	ds_read_b64 v[190:191], v249 offset:16
	ds_read_b64 v[184:185], v249 offset:32
	ds_read_b64 v[186:187], v249 offset:48
	ds_read_b64 v[180:181], v249 offset:64
	ds_read_b64 v[182:183], v249 offset:80
	ds_read_b64 v[176:177], v249 offset:96
	ds_read_b64 v[178:179], v249 offset:112
	ds_read_b64 v[172:173], v249 offset:0x1100
	ds_read_b64 v[174:175], v249 offset:0x1110
	ds_read_b64 v[168:169], v249 offset:0x1120
	ds_read_b64 v[170:171], v249 offset:0x1130
	ds_read_b64 v[164:165], v249 offset:0x1140
	ds_read_b64 v[166:167], v249 offset:0x1150
	ds_read_b64 v[160:161], v249 offset:0x1160
	ds_read_b64 v[162:163], v249 offset:0x1170
	v_max3_f32 v65, v112, v113, v114
	v_max3_f32 v65, v65, v115, v116
	v_max3_f32 v65, v65, v117, v118
	v_max3_f32 v65, v65, v119, v120
	v_max3_f32 v65, v65, v121, v122
	v_max3_f32 v65, v65, v123, v124
	v_max3_f32 v65, v65, v125, v126
	v_max_f32_e32 v65, v65, v127
	v_max3_f32 v64, v96, v97, v98
	v_max3_f32 v66, v99, v100, v101
	v_max3_f32 v64, v64, v102, v103
	v_max3_f32 v66, v66, v104, v105
	v_max3_f32 v64, v64, v106, v107
	v_max3_f32 v66, v66, v108, v109
	v_max3_f32 v64, v64, v110, v111
	v_max3_f32 v64, v64, v66, v65
	v_mov_b32_e32 v65, v64
	s_nop 1
	v_permlane32_swap_b32_e32 v64, v65
	v_max_f32_e32 v64, v64, v65
	v_cmp_lt_f32_e32 vcc, s80, v64
	s_cbranch_vccz .LBB0_981
	v_max_f32_e32 v80, 0, v64
	v_exp_f32_e64 v64, -v80
	s_nop 0
	v_mov_b32_e32 v81, v64
	v_pk_mul_f32 v[14:15], v[14:15], v[64:65] op_sel_hi:[1,0]
	v_pk_mul_f32 v[12:13], v[12:13], v[64:65] op_sel_hi:[1,0]
	v_pk_mul_f32 v[10:11], v[10:11], v[64:65] op_sel_hi:[1,0]
	v_pk_mul_f32 v[8:9], v[8:9], v[64:65] op_sel_hi:[1,0]
	v_pk_mul_f32 v[6:7], v[6:7], v[64:65] op_sel_hi:[1,0]
	v_pk_mul_f32 v[4:5], v[4:5], v[64:65] op_sel_hi:[1,0]
	v_pk_mul_f32 v[2:3], v[2:3], v[64:65] op_sel_hi:[1,0]
	v_pk_mul_f32 v[0:1], v[0:1], v[64:65] op_sel_hi:[1,0]
	v_pk_mul_f32 v[62:63], v[62:63], v[64:65] op_sel_hi:[1,0]
	v_pk_mul_f32 v[60:61], v[60:61], v[64:65] op_sel_hi:[1,0]
	v_pk_mul_f32 v[58:59], v[58:59], v[64:65] op_sel_hi:[1,0]
	v_pk_mul_f32 v[56:57], v[56:57], v[64:65] op_sel_hi:[1,0]
	v_pk_mul_f32 v[54:55], v[54:55], v[64:65] op_sel_hi:[1,0]
	v_pk_mul_f32 v[52:53], v[52:53], v[64:65] op_sel_hi:[1,0]
	v_pk_mul_f32 v[50:51], v[50:51], v[64:65] op_sel_hi:[1,0]
	v_pk_mul_f32 v[48:49], v[48:49], v[64:65] op_sel_hi:[1,0]
	v_pk_mul_f32 v[46:47], v[46:47], v[64:65] op_sel_hi:[1,0]
	v_pk_mul_f32 v[44:45], v[44:45], v[64:65] op_sel_hi:[1,0]
	v_pk_mul_f32 v[42:43], v[42:43], v[64:65] op_sel_hi:[1,0]
	v_pk_mul_f32 v[40:41], v[40:41], v[64:65] op_sel_hi:[1,0]
	v_pk_mul_f32 v[38:39], v[38:39], v[64:65] op_sel_hi:[1,0]
	v_pk_mul_f32 v[36:37], v[36:37], v[64:65] op_sel_hi:[1,0]
	v_pk_mul_f32 v[34:35], v[34:35], v[64:65] op_sel_hi:[1,0]
	v_pk_mul_f32 v[32:33], v[32:33], v[64:65] op_sel_hi:[1,0]
	v_pk_mul_f32 v[30:31], v[30:31], v[64:65] op_sel_hi:[1,0]
	v_pk_mul_f32 v[28:29], v[28:29], v[64:65] op_sel_hi:[1,0]
	v_pk_mul_f32 v[26:27], v[26:27], v[64:65] op_sel_hi:[1,0]
	v_pk_mul_f32 v[24:25], v[24:25], v[64:65] op_sel_hi:[1,0]
	v_pk_mul_f32 v[22:23], v[22:23], v[64:65] op_sel_hi:[1,0]
	v_pk_mul_f32 v[20:21], v[20:21], v[64:65] op_sel_hi:[1,0]
	v_pk_mul_f32 v[18:19], v[18:19], v[64:65] op_sel_hi:[1,0]
	v_pk_mul_f32 v[16:17], v[16:17], v[64:65] op_sel_hi:[1,0]
	v_pk_add_f32 v[212:213], v[210:211], v[80:81]
	v_pk_mul_f32 v[64:65], v[210:211], v[80:81]
	v_pk_add_f32 v[112:113], v[112:113], v[80:81] op_sel_hi:[1,0] neg_lo:[0,1] neg_hi:[0,1]
	v_mov_b32_e32 v213, v65
	v_pk_add_f32 v[64:65], v[212:213], 0 neg_lo:[1,1] neg_hi:[1,1]
	v_pk_add_f32 v[96:97], v[96:97], v[80:81] op_sel_hi:[1,0] neg_lo:[0,1] neg_hi:[0,1]
	v_pk_add_f32 v[114:115], v[114:115], v[80:81] op_sel_hi:[1,0] neg_lo:[0,1] neg_hi:[0,1]
	v_pk_add_f32 v[98:99], v[98:99], v[80:81] op_sel_hi:[1,0] neg_lo:[0,1] neg_hi:[0,1]
	v_pk_add_f32 v[116:117], v[116:117], v[80:81] op_sel_hi:[1,0] neg_lo:[0,1] neg_hi:[0,1]
	v_pk_add_f32 v[100:101], v[100:101], v[80:81] op_sel_hi:[1,0] neg_lo:[0,1] neg_hi:[0,1]
	v_pk_add_f32 v[118:119], v[118:119], v[80:81] op_sel_hi:[1,0] neg_lo:[0,1] neg_hi:[0,1]
	v_pk_add_f32 v[102:103], v[102:103], v[80:81] op_sel_hi:[1,0] neg_lo:[0,1] neg_hi:[0,1]
	v_pk_add_f32 v[120:121], v[120:121], v[80:81] op_sel_hi:[1,0] neg_lo:[0,1] neg_hi:[0,1]
	v_pk_add_f32 v[104:105], v[104:105], v[80:81] op_sel_hi:[1,0] neg_lo:[0,1] neg_hi:[0,1]
	v_pk_add_f32 v[122:123], v[122:123], v[80:81] op_sel_hi:[1,0] neg_lo:[0,1] neg_hi:[0,1]
	v_pk_add_f32 v[106:107], v[106:107], v[80:81] op_sel_hi:[1,0] neg_lo:[0,1] neg_hi:[0,1]
	v_pk_add_f32 v[124:125], v[124:125], v[80:81] op_sel_hi:[1,0] neg_lo:[0,1] neg_hi:[0,1]
	v_pk_add_f32 v[108:109], v[108:109], v[80:81] op_sel_hi:[1,0] neg_lo:[0,1] neg_hi:[0,1]
	v_mov_b32_e32 v65, v64
	v_mov_b32_e32 v66, v64
	v_mov_b32_e32 v67, v64
	v_mov_b32_e32 v68, v64
	v_mov_b32_e32 v69, v64
	v_mov_b32_e32 v70, v64
	v_mov_b32_e32 v71, v64
	v_mov_b32_e32 v72, v64
	v_mov_b32_e32 v73, v64
	v_mov_b32_e32 v74, v64
	v_mov_b32_e32 v75, v64
	v_mov_b32_e32 v76, v64
	v_mov_b32_e32 v77, v64
	v_mov_b32_e32 v78, v64
	v_mov_b32_e32 v79, v64
	v_pk_add_f32 v[126:127], v[126:127], v[80:81] op_sel_hi:[1,0] neg_lo:[0,1] neg_hi:[0,1]
	v_pk_add_f32 v[110:111], v[110:111], v[80:81] op_sel_hi:[1,0] neg_lo:[0,1] neg_hi:[0,1]
	v_mov_b32_e32 v80, v64
	v_mov_b32_e32 v81, v64
	v_mov_b32_e32 v82, v64
	v_mov_b32_e32 v83, v64
	v_mov_b32_e32 v84, v64
	v_mov_b32_e32 v85, v64
	v_mov_b32_e32 v86, v64
	v_mov_b32_e32 v87, v64
	v_mov_b32_e32 v88, v64
	v_mov_b32_e32 v89, v64
	v_mov_b32_e32 v90, v64
	v_mov_b32_e32 v91, v64
	v_mov_b32_e32 v92, v64
	v_mov_b32_e32 v93, v64
	v_mov_b32_e32 v94, v64
	v_mov_b32_e32 v95, v64
	v_mov_b32_e32 v210, v212
	s_branch .LBB0_982
